# headnorm_rows loops (K/ks/kw/memK head RMSNorm): gains loaded once before the loop, next row prefetched at the top of each iteration and copied in after the store (2 wait states after the dwordx4 stor
# baseline (speedup 1.0000x reference)
; #define TIDX launder((int)threadIdx.x)
; DI float bf2f(bf16_t v) { return __uint_as_float(((unsigned)v) << 16); }
; DI unsigned pk2(float lo, float hi) { const f32x2g f = {lo, hi}; const hwbf16x2g r = __builtin_convertvector(f, hwbf16x2g); return __builtin_bit_cast(unsigned, r); }
; DI float shx(float v, int mask) { return __int_as_float(__builtin_amdgcn_ds_bpermute((lane_now() ^ mask) << 2, __float_as_int(v))); }
; DI void headnorm_rows(bf16_t* buf, int rows, const float* __restrict__ gain, int item0, int nitems_total) {
;   const int lane = TIDX & 63, gw = blockIdx.x * 8 + (TIDX >> 6), nw = gridDim.x * 8;
;   const int sub = lane >> 4, l16 = lane & 15;
;   (void)item0; (void)nitems_total;
;   for (int it = gw; it < rows / 4; it += nw) {
;     bf16_t* rp = buf + (size_t)(it * 4 + sub) * 128 + l16 * 8;
;     bf16x8 raw = *(const bf16x8*)rp;
;     float f[8], s = 0.f;
; #pragma unroll
;     for (int e = 0; e < 8; ++e) { f[e] = bf2f((bf16_t)raw[e]); s += f[e] * f[e]; }
;     s += shx(s, 1); s += shx(s, 2); s += shx(s, 4); s += shx(s, 8);
;     const float rs = rsqrtf(s * (1.f / 128.f) + EPS_);
;     u32x4 o;
;     o.x = pk2(f[0] * rs * gain[l16 * 8 + 0], f[1] * rs * gain[l16 * 8 + 1]); o.y = pk2(f[2] * rs * gain[l16 * 8 + 2], f[3] * rs * gain[l16 * 8 + 3]);
;     o.z = pk2(f[4] * rs * gain[l16 * 8 + 4], f[5] * rs * gain[l16 * 8 + 5]); o.w = pk2(f[6] * rs * gain[l16 * 8 + 6], f[7] * rs * gain[l16 * 8 + 7]);
;     *(u32x4*)rp = o;
;   }
; DI void run_phase(const Params& p0, int ph) {
;     ...
;         if (KEYOK(19)) {
;         headnorm_rows((bf16_t*)(ws + O_KS), 8 * T_, p.in[16] + (e * 3 + 1) * 128, 0, 0);
;         headnorm_rows((bf16_t*)(ws + O_KW), 8 * T_, p.in[16] + (e * 3 + 2) * 128, 0, 0);
.LBB0_342:
	s_andn2_b64 vcc, exec, s[0:1]
	s_mov_b64 s[2:3], 0
	s_cbranch_vccnz .LBB0_374
	v_readlane_b32 s0, v254, 24
	s_cmp_gt_i32 s0, 1
	s_mov_b64 s[0:1], -1
	s_cbranch_scc0 .LBB0_372
	v_readlane_b32 s2, v254, 16
	v_readlane_b32 s3, v254, 17
	s_and_b64 vcc, exec, s[2:3]
	s_cbranch_vccz .LBB0_361
	v_readlane_b32 s0, v254, 20
	v_readlane_b32 s1, v254, 21
	v_mov_b32_e32 v2, v199
	v_mov_b32_e32 v0, v199
	v_readlane_b32 s1, v250, 11
	v_ashrrev_i32_e32 v6, 6, v0
	s_mulk_i32 s0, 0x180
	v_add_u32_e32 v0, s1, v6
	v_cmp_gt_i32_e32 vcc, s81, v0
	s_and_saveexec_b64 s[2:3], vcc
	v_readlane_b32 s8, v252, 43
	v_readlane_b32 s9, v252, 44
	s_mov_b32 s9, 0x800000
	s_movk_i32 s10, 0x1fff
	s_cbranch_execz .LBB0_348
	v_bfe_u32 v7, v2, 4, 2
	s_ashr_i32 s1, s0, 31
	v_lshlrev_b32_e32 v2, 3, v2
	s_lshl_b64 s[4:5], s[0:1], 2
	v_readlane_b32 s12, v253, 30
	v_and_b32_e32 v4, 0x78, v2
	v_readlane_b32 s6, v253, 48
	v_readlane_b32 s13, v253, 31
	s_add_u32 s4, s12, s4
	v_lshlrev_b32_e32 v2, 1, v4
	s_waitcnt lgkmcnt(0)
	v_mov_b32_e32 v3, v1
	v_readlane_b32 s7, v253, 49
	s_addc_u32 s5, s13, s5
	v_lshlrev_b32_e32 v4, 2, v4
	v_lshl_add_u64 v[2:3], s[6:7], 0, v[2:3]
	s_mov_b64 s[6:7], 0x28165000
	v_mov_b32_e32 v5, v1
	v_lshlrev_b32_e32 v6, 2, v6
	v_readlane_b32 s1, v252, 35
	v_lshl_add_u64 v[2:3], v[2:3], 0, s[6:7]
	v_lshl_add_u64 v[4:5], s[4:5], 0, v[4:5]
	v_add3_u32 v6, s1, v6, v7
	v_readlane_b32 s1, v252, 36
	s_mov_b64 s[4:5], 0
	v_readlane_b32 s14, v253, 32
	v_readlane_b32 s15, v253, 33
	v_readlane_b32 s16, v253, 34
	v_readlane_b32 s17, v253, 35
	v_readlane_b32 s18, v253, 36
	v_readlane_b32 s19, v253, 37
	v_readlane_b32 s20, v253, 38
	v_readlane_b32 s21, v253, 39
	v_readlane_b32 s22, v253, 40
	v_readlane_b32 s23, v253, 41
	v_readlane_b32 s24, v253, 42
	v_readlane_b32 s25, v253, 43
	v_readlane_b32 s26, v253, 44
	v_readlane_b32 s27, v253, 45
	global_load_dwordx4 v[44:47], v[4:5], off offset:528
	global_load_dwordx4 v[48:51], v[4:5], off offset:512
	v_ashrrev_i32_e32 v7, 31, v6
	v_lshlrev_b64 v[8:9], 8, v[6:7]
	v_lshl_add_u64 v[18:19], v[2:3], 0, v[8:9]
	global_load_dwordx4 v[8:11], v[18:19], off
	s_waitcnt vmcnt(0)
.LBB0_347:
	v_add_u32_e32 v38, s1, v6
	v_ashrrev_i32_e32 v39, 31, v38
	v_lshlrev_b64 v[38:39], 8, v[38:39]
	v_lshl_add_u64 v[52:53], v[2:3], 0, v[38:39]
	global_load_dwordx4 v[40:43], v[52:53], off
	v_mov_b32_e32 v7, v199
	v_mov_b32_e32 v12, v199
	v_add_u32_e32 v0, s8, v0
	v_lshlrev_b32_e32 v12, 2, v12
	v_bitop3_b32 v34, v12, 8, v193 bitop3:0x6c
	v_mov_b32_e32 v12, v199
	v_lshlrev_b32_e32 v7, 2, v7
	v_lshlrev_b32_e32 v12, 2, v12
	v_bitop3_b32 v35, v12, 16, v193 bitop3:0x6c
	v_mov_b32_e32 v12, v199
	v_bitop3_b32 v7, v7, 4, v193 bitop3:0x6c
	v_lshlrev_b32_e32 v12, 2, v12
	v_bitop3_b32 v36, v12, 32, v193 bitop3:0x6c
	v_add_u32_e32 v6, s1, v6
	v_and_b32_e32 v21, 0xffff0000, v11
	v_lshlrev_b32_e32 v20, 16, v11
	v_and_b32_e32 v25, 0xffff0000, v10
	v_lshlrev_b32_e32 v24, 16, v10
	v_and_b32_e32 v29, 0xffff0000, v9
	v_lshlrev_b32_e32 v28, 16, v9
	v_and_b32_e32 v9, 0xffff0000, v8
	v_lshlrev_b32_e32 v8, 16, v8
	v_pk_mul_f32 v[32:33], v[8:9], v[8:9]
	v_pk_mul_f32 v[30:31], v[28:29], v[28:29]
	v_add_f32_e32 v32, v32, v33
	v_add_f32_e32 v30, v30, v32
	v_pk_mul_f32 v[26:27], v[24:25], v[24:25]
	v_add_f32_e32 v30, v31, v30
	v_add_f32_e32 v26, v26, v30
	v_pk_mul_f32 v[22:23], v[20:21], v[20:21]
	v_add_f32_e32 v26, v27, v26
	v_add_f32_e32 v22, v22, v26
	v_add_f32_e32 v22, v23, v22
	ds_bpermute_b32 v7, v7, v22
	s_waitcnt lgkmcnt(0)
	v_add_f32_e32 v7, v22, v7
	ds_bpermute_b32 v22, v34, v7
	s_waitcnt lgkmcnt(0)
	v_add_f32_e32 v7, v7, v22
	ds_bpermute_b32 v22, v35, v7
	s_waitcnt lgkmcnt(0)
	v_add_f32_e32 v7, v7, v22
	ds_bpermute_b32 v22, v36, v7
	s_waitcnt lgkmcnt(0)
	v_add_f32_e32 v7, v7, v22
	v_fmamk_f32 v7, v7, 0x3c000000, v249
	v_cmp_gt_f32_e32 vcc, s9, v7
	v_mul_f32_e32 v22, 0x4b800000, v7
	s_nop 0
	v_cndmask_b32_e32 v7, v7, v22, vcc
	v_rsq_f32_e32 v7, v7
	s_nop 0
	v_mul_f32_e32 v22, 0x45800000, v7
	v_cndmask_b32_e32 v22, v7, v22, vcc
	v_pk_mul_f32 v[8:9], v[22:23], v[8:9] op_sel_hi:[0,1]
	v_cmp_lt_i32_e32 vcc, s10, v0
	s_or_b64 s[4:5], vcc, s[4:5]
	v_pk_mul_f32 v[8:9], v[48:49], v[8:9]
	v_pk_mul_f32 v[14:15], v[22:23], v[28:29] op_sel_hi:[0,1]
	v_pk_mul_f32 v[14:15], v[50:51], v[14:15]
	v_cvt_pk_bf16_f32 v8, v8, v9
	v_cvt_pk_bf16_f32 v9, v14, v15
	v_pk_mul_f32 v[14:15], v[22:23], v[24:25] op_sel_hi:[0,1]
	v_pk_mul_f32 v[10:11], v[44:45], v[14:15]
	v_pk_mul_f32 v[14:15], v[22:23], v[20:21] op_sel_hi:[0,1]
	v_pk_mul_f32 v[12:13], v[46:47], v[14:15]
	v_cvt_pk_bf16_f32 v10, v10, v11
	v_cvt_pk_bf16_f32 v11, v12, v13
	global_store_dwordx4 v[18:19], v[8:11], off
	s_waitcnt vmcnt(1)
	s_nop 1
	v_mov_b32_e32 v8, v40
	v_mov_b32_e32 v9, v41
	v_mov_b32_e32 v10, v42
	v_mov_b32_e32 v11, v43
	v_mov_b32_e32 v18, v52
	v_mov_b32_e32 v19, v53
	s_andn2_b64 exec, exec, s[4:5]
	s_cbranch_execnz .LBB0_347
; #define TIDX launder((int)threadIdx.x)
; DI float bf2f(bf16_t v) { return __uint_as_float(((unsigned)v) << 16); }
; DI unsigned pk2(float lo, float hi) { const f32x2g f = {lo, hi}; const hwbf16x2g r = __builtin_convertvector(f, hwbf16x2g); return __builtin_bit_cast(unsigned, r); }
; DI float shx(float v, int mask) { return __int_as_float(__builtin_amdgcn_ds_bpermute((lane_now() ^ mask) << 2, __float_as_int(v))); }
; DI void headnorm_rows(bf16_t* buf, int rows, const float* __restrict__ gain, int item0, int nitems_total) {
;   const int lane = TIDX & 63, gw = blockIdx.x * 8 + (TIDX >> 6), nw = gridDim.x * 8;
;   const int sub = lane >> 4, l16 = lane & 15;
;   (void)item0; (void)nitems_total;
;   for (int it = gw; it < rows / 4; it += nw) {
;     bf16_t* rp = buf + (size_t)(it * 4 + sub) * 128 + l16 * 8;
;     bf16x8 raw = *(const bf16x8*)rp;
;     float f[8], s = 0.f;
; #pragma unroll
;     for (int e = 0; e < 8; ++e) { f[e] = bf2f((bf16_t)raw[e]); s += f[e] * f[e]; }
;     s += shx(s, 1); s += shx(s, 2); s += shx(s, 4); s += shx(s, 8);
;     const float rs = rsqrtf(s * (1.f / 128.f) + EPS_);
;     u32x4 o;
;     o.x = pk2(f[0] * rs * gain[l16 * 8 + 0], f[1] * rs * gain[l16 * 8 + 1]); o.y = pk2(f[2] * rs * gain[l16 * 8 + 2], f[3] * rs * gain[l16 * 8 + 3]);
;     o.z = pk2(f[4] * rs * gain[l16 * 8 + 4], f[5] * rs * gain[l16 * 8 + 5]); o.w = pk2(f[6] * rs * gain[l16 * 8 + 6], f[7] * rs * gain[l16 * 8 + 7]);
;     *(u32x4*)rp = o;
;   }
; DI void run_phase(const Params& p0, int ph) {
;     ...
;         headnorm_rows((bf16_t*)(ws + O_KW), 8 * T_, p.in[16] + (e * 3 + 2) * 128, 0, 0);
.LBB0_348:
	s_or_b64 exec, exec, s[2:3]
	v_mov_b32_e32 v2, v199
	v_mov_b32_e32 v0, v199
	v_readlane_b32 s1, v250, 11
	v_ashrrev_i32_e32 v6, 6, v0
	s_nop 0
	v_add_u32_e32 v0, s1, v6
	v_cmp_gt_i32_e32 vcc, s81, v0
	s_and_saveexec_b64 s[2:3], vcc
	v_readlane_b32 s6, v252, 43
	v_readlane_b32 s7, v252, 44
	v_readlane_b32 s7, v252, 36
	s_mov_b32 s8, 0x800000
	s_cbranch_execz .LBB0_351
	s_ashr_i32 s1, s0, 31
	v_bfe_u32 v7, v2, 4, 2
	s_lshl_b64 s[0:1], s[0:1], 2
	v_readlane_b32 s12, v253, 30
	v_lshlrev_b32_e32 v2, 3, v2
	v_readlane_b32 s13, v253, 31
	s_add_u32 s0, s12, s0
	v_and_b32_e32 v4, 0x78, v2
	v_readlane_b32 s4, v253, 48
	s_addc_u32 s1, s13, s1
	v_lshlrev_b32_e32 v2, 1, v4
	s_waitcnt lgkmcnt(0)
	v_mov_b32_e32 v3, v1
	v_readlane_b32 s5, v253, 49
	v_lshlrev_b32_e32 v4, 2, v4
	v_mov_b32_e32 v5, v1
	v_lshl_add_u64 v[2:3], s[4:5], 0, v[2:3]
	s_mov_b64 s[4:5], 0x28965000
	v_lshl_add_u64 v[4:5], s[0:1], 0, v[4:5]
	v_lshlrev_b32_e32 v6, 2, v6
	v_readlane_b32 s0, v252, 35
	v_lshl_add_u64 v[2:3], v[2:3], 0, s[4:5]
	v_readlane_b32 s14, v253, 32
	v_add3_u32 v6, s0, v6, v7
	s_mov_b64 s[0:1], 0
	v_readlane_b32 s15, v253, 33
	v_readlane_b32 s16, v253, 34
	v_readlane_b32 s17, v253, 35
	v_readlane_b32 s18, v253, 36
	v_readlane_b32 s19, v253, 37
	v_readlane_b32 s20, v253, 38
	v_readlane_b32 s21, v253, 39
	v_readlane_b32 s22, v253, 40
	v_readlane_b32 s23, v253, 41
	v_readlane_b32 s24, v253, 42
	v_readlane_b32 s25, v253, 43
	v_readlane_b32 s26, v253, 44
	v_readlane_b32 s27, v253, 45
	global_load_dwordx4 v[44:47], v[4:5], off offset:1040
	global_load_dwordx4 v[48:51], v[4:5], off offset:1024
	v_ashrrev_i32_e32 v7, 31, v6
	v_lshlrev_b64 v[8:9], 8, v[6:7]
	v_lshl_add_u64 v[18:19], v[2:3], 0, v[8:9]
	global_load_dwordx4 v[8:11], v[18:19], off
	s_waitcnt vmcnt(0)
.LBB0_350:
	v_add_u32_e32 v38, s7, v6
	v_ashrrev_i32_e32 v39, 31, v38
	v_lshlrev_b64 v[38:39], 8, v[38:39]
	v_lshl_add_u64 v[52:53], v[2:3], 0, v[38:39]
	global_load_dwordx4 v[40:43], v[52:53], off
	v_mov_b32_e32 v7, v199
	v_mov_b32_e32 v12, v199
	v_add_u32_e32 v0, s6, v0
	v_lshlrev_b32_e32 v12, 2, v12
	v_bitop3_b32 v34, v12, 8, v193 bitop3:0x6c
	v_mov_b32_e32 v12, v199
	v_lshlrev_b32_e32 v7, 2, v7
	v_lshlrev_b32_e32 v12, 2, v12
	v_bitop3_b32 v35, v12, 16, v193 bitop3:0x6c
	v_mov_b32_e32 v12, v199
	v_bitop3_b32 v7, v7, 4, v193 bitop3:0x6c
	v_lshlrev_b32_e32 v12, 2, v12
	v_bitop3_b32 v36, v12, 32, v193 bitop3:0x6c
	v_add_u32_e32 v6, s7, v6
	v_and_b32_e32 v21, 0xffff0000, v11
	v_lshlrev_b32_e32 v20, 16, v11
	v_and_b32_e32 v25, 0xffff0000, v10
	v_lshlrev_b32_e32 v24, 16, v10
	v_and_b32_e32 v29, 0xffff0000, v9
	v_lshlrev_b32_e32 v28, 16, v9
	v_and_b32_e32 v9, 0xffff0000, v8
	v_lshlrev_b32_e32 v8, 16, v8
	v_pk_mul_f32 v[32:33], v[8:9], v[8:9]
	v_pk_mul_f32 v[30:31], v[28:29], v[28:29]
	v_add_f32_e32 v32, v32, v33
	v_add_f32_e32 v30, v30, v32
	v_pk_mul_f32 v[26:27], v[24:25], v[24:25]
	v_add_f32_e32 v30, v31, v30
	v_add_f32_e32 v26, v26, v30
	v_pk_mul_f32 v[22:23], v[20:21], v[20:21]
	v_add_f32_e32 v26, v27, v26
	v_add_f32_e32 v22, v22, v26
	v_add_f32_e32 v22, v23, v22
	ds_bpermute_b32 v7, v7, v22
	s_waitcnt lgkmcnt(0)
	v_add_f32_e32 v7, v22, v7
	ds_bpermute_b32 v22, v34, v7
	s_waitcnt lgkmcnt(0)
	v_add_f32_e32 v7, v7, v22
	ds_bpermute_b32 v22, v35, v7
	s_waitcnt lgkmcnt(0)
	v_add_f32_e32 v7, v7, v22
	ds_bpermute_b32 v22, v36, v7
	s_waitcnt lgkmcnt(0)
	v_add_f32_e32 v7, v7, v22
	v_fmamk_f32 v7, v7, 0x3c000000, v249
	v_cmp_gt_f32_e32 vcc, s8, v7
	v_mul_f32_e32 v22, 0x4b800000, v7
	s_nop 0
	v_cndmask_b32_e32 v7, v7, v22, vcc
	v_rsq_f32_e32 v7, v7
	s_nop 0
	v_mul_f32_e32 v22, 0x45800000, v7
	v_cndmask_b32_e32 v22, v7, v22, vcc
	v_pk_mul_f32 v[8:9], v[22:23], v[8:9] op_sel_hi:[0,1]
	v_cmp_lt_i32_e32 vcc, s10, v0
	s_or_b64 s[0:1], vcc, s[0:1]
	v_pk_mul_f32 v[8:9], v[48:49], v[8:9]
	v_pk_mul_f32 v[14:15], v[22:23], v[28:29] op_sel_hi:[0,1]
	v_pk_mul_f32 v[14:15], v[50:51], v[14:15]
	v_cvt_pk_bf16_f32 v8, v8, v9
	v_cvt_pk_bf16_f32 v9, v14, v15
	v_pk_mul_f32 v[14:15], v[22:23], v[24:25] op_sel_hi:[0,1]
	v_pk_mul_f32 v[10:11], v[44:45], v[14:15]
	v_pk_mul_f32 v[14:15], v[22:23], v[20:21] op_sel_hi:[0,1]
	v_pk_mul_f32 v[12:13], v[46:47], v[14:15]
	v_cvt_pk_bf16_f32 v10, v10, v11
	v_cvt_pk_bf16_f32 v11, v12, v13
	global_store_dwordx4 v[18:19], v[8:11], off
	s_waitcnt vmcnt(1)
	s_nop 1
	v_mov_b32_e32 v8, v40
	v_mov_b32_e32 v9, v41
	v_mov_b32_e32 v10, v42
	v_mov_b32_e32 v11, v43
	v_mov_b32_e32 v18, v52
	v_mov_b32_e32 v19, v53
	s_andn2_b64 exec, exec, s[0:1]
	s_cbranch_execnz .LBB0_350

; #define TIDX launder((int)threadIdx.x)
; DI float bf2f(bf16_t v) { return __uint_as_float(((unsigned)v) << 16); }
; DI unsigned pk2(float lo, float hi) { const f32x2g f = {lo, hi}; const hwbf16x2g r = __builtin_convertvector(f, hwbf16x2g); return __builtin_bit_cast(unsigned, r); }
; DI float shx(float v, int mask) { return __int_as_float(__builtin_amdgcn_ds_bpermute((lane_now() ^ mask) << 2, __float_as_int(v))); }
; DI void headnorm_rows(bf16_t* buf, int rows, const float* __restrict__ gain, int item0, int nitems_total) {
;   const int lane = TIDX & 63, gw = blockIdx.x * 8 + (TIDX >> 6), nw = gridDim.x * 8;
;   const int sub = lane >> 4, l16 = lane & 15;
;   (void)item0; (void)nitems_total;
;   for (int it = gw; it < rows / 4; it += nw) {
;     bf16_t* rp = buf + (size_t)(it * 4 + sub) * 128 + l16 * 8;
;     bf16x8 raw = *(const bf16x8*)rp;
;     float f[8], s = 0.f;
; #pragma unroll
;     for (int e = 0; e < 8; ++e) { f[e] = bf2f((bf16_t)raw[e]); s += f[e] * f[e]; }
;     s += shx(s, 1); s += shx(s, 2); s += shx(s, 4); s += shx(s, 8);
;     const float rs = rsqrtf(s * (1.f / 128.f) + EPS_);
;     u32x4 o;
;     o.x = pk2(f[0] * rs * gain[l16 * 8 + 0], f[1] * rs * gain[l16 * 8 + 1]); o.y = pk2(f[2] * rs * gain[l16 * 8 + 2], f[3] * rs * gain[l16 * 8 + 3]);
;     o.z = pk2(f[4] * rs * gain[l16 * 8 + 4], f[5] * rs * gain[l16 * 8 + 5]); o.w = pk2(f[6] * rs * gain[l16 * 8 + 6], f[7] * rs * gain[l16 * 8 + 7]);
;     *(u32x4*)rp = o;
;   }
; DI void run_phase(const Params& p0, int ph) {
;     ...
;         headnorm_rows((bf16_t*)(ws + E_FK), 16 * T_, p.in[10] + e * 128, 0, 0);
.LBB0_361:
	s_and_b64 vcc, exec, s[0:1]
	s_cbranch_vccz .LBB0_371
	v_mov_b32_e32 v2, v199
	v_mov_b32_e32 v0, v199
	v_readlane_b32 s0, v250, 11
	v_ashrrev_i32_e32 v6, 6, v0
	s_nop 0
	v_add_u32_e32 v0, s0, v6
	s_movk_i32 s0, 0x4000
	v_cmp_gt_i32_e32 vcc, s0, v0
	s_and_saveexec_b64 s[0:1], vcc
	v_readlane_b32 s6, v252, 43
	v_readlane_b32 s7, v252, 44
	v_readlane_b32 s7, v252, 36
	s_mov_b32 s8, 0x800000
	s_cbranch_execz .LBB0_365
	v_readlane_b32 s2, v254, 20
	v_readlane_b32 s3, v254, 21
	s_lshl_b32 s2, s2, 7
	s_ashr_i32 s3, s2, 31
	v_readlane_b32 s12, v253, 14
	v_bfe_u32 v7, v2, 4, 2
	s_lshl_b64 s[2:3], s[2:3], 2
	v_readlane_b32 s16, v253, 18
	v_lshlrev_b32_e32 v2, 3, v2
	v_readlane_b32 s17, v253, 19
	s_add_u32 s2, s16, s2
	v_and_b32_e32 v4, 0x78, v2
	v_readlane_b32 s4, v253, 48
	s_addc_u32 s3, s17, s3
	v_lshlrev_b32_e32 v2, 1, v4
	s_waitcnt lgkmcnt(0)
	v_mov_b32_e32 v3, v1
	v_readlane_b32 s5, v253, 49
	v_lshlrev_b32_e32 v4, 2, v4
	v_mov_b32_e32 v5, v1
	v_lshl_add_u64 v[2:3], s[4:5], 0, v[2:3]
	s_mov_b64 s[4:5], 0x26145000
	v_lshl_add_u64 v[4:5], s[2:3], 0, v[4:5]
	v_lshlrev_b32_e32 v6, 2, v6
	v_readlane_b32 s2, v252, 35
	v_lshl_add_u64 v[2:3], v[2:3], 0, s[4:5]
	v_readlane_b32 s13, v253, 15
	v_add3_u32 v6, s2, v6, v7
	s_mov_b64 s[2:3], 0
	v_readlane_b32 s14, v253, 16
	v_readlane_b32 s15, v253, 17
	v_readlane_b32 s18, v253, 20
	v_readlane_b32 s19, v253, 21
	v_readlane_b32 s20, v253, 22
	v_readlane_b32 s21, v253, 23
	v_readlane_b32 s22, v253, 24
	v_readlane_b32 s23, v253, 25
	v_readlane_b32 s24, v253, 26
	v_readlane_b32 s25, v253, 27
	v_readlane_b32 s26, v253, 28
	v_readlane_b32 s27, v253, 29
	global_load_dwordx4 v[44:47], v[4:5], off offset:16
	global_load_dwordx4 v[48:51], v[4:5], off
	v_ashrrev_i32_e32 v7, 31, v6
	v_lshlrev_b64 v[8:9], 8, v[6:7]
	v_lshl_add_u64 v[18:19], v[2:3], 0, v[8:9]
	global_load_dwordx4 v[8:11], v[18:19], off
	s_waitcnt vmcnt(0)
.LBB0_364:
	v_add_u32_e32 v38, s7, v6
	v_ashrrev_i32_e32 v39, 31, v38
	v_lshlrev_b64 v[38:39], 8, v[38:39]
	v_lshl_add_u64 v[52:53], v[2:3], 0, v[38:39]
	global_load_dwordx4 v[40:43], v[52:53], off
	v_mov_b32_e32 v7, v199
	v_mov_b32_e32 v12, v199
	v_add_u32_e32 v0, s6, v0
	v_lshlrev_b32_e32 v12, 2, v12
	v_bitop3_b32 v34, v12, 8, v193 bitop3:0x6c
	v_mov_b32_e32 v12, v199
	v_lshlrev_b32_e32 v7, 2, v7
	v_lshlrev_b32_e32 v12, 2, v12
	v_bitop3_b32 v35, v12, 16, v193 bitop3:0x6c
	v_mov_b32_e32 v12, v199
	v_bitop3_b32 v7, v7, 4, v193 bitop3:0x6c
	v_lshlrev_b32_e32 v12, 2, v12
	v_bitop3_b32 v36, v12, 32, v193 bitop3:0x6c
	s_movk_i32 s4, 0x3fff
	v_add_u32_e32 v6, s7, v6
	v_and_b32_e32 v21, 0xffff0000, v11
	v_lshlrev_b32_e32 v20, 16, v11
	v_and_b32_e32 v25, 0xffff0000, v10
	v_lshlrev_b32_e32 v24, 16, v10
	v_and_b32_e32 v29, 0xffff0000, v9
	v_lshlrev_b32_e32 v28, 16, v9
	v_and_b32_e32 v9, 0xffff0000, v8
	v_lshlrev_b32_e32 v8, 16, v8
	v_pk_mul_f32 v[32:33], v[8:9], v[8:9]
	v_pk_mul_f32 v[30:31], v[28:29], v[28:29]
	v_add_f32_e32 v32, v32, v33
	v_add_f32_e32 v30, v30, v32
	v_pk_mul_f32 v[26:27], v[24:25], v[24:25]
	v_add_f32_e32 v30, v31, v30
	v_add_f32_e32 v26, v26, v30
	v_pk_mul_f32 v[22:23], v[20:21], v[20:21]
	v_add_f32_e32 v26, v27, v26
	v_add_f32_e32 v22, v22, v26
	v_add_f32_e32 v22, v23, v22
	ds_bpermute_b32 v7, v7, v22
	s_waitcnt lgkmcnt(0)
	v_add_f32_e32 v7, v22, v7
	ds_bpermute_b32 v22, v34, v7
	s_waitcnt lgkmcnt(0)
	v_add_f32_e32 v7, v7, v22
	ds_bpermute_b32 v22, v35, v7
	s_waitcnt lgkmcnt(0)
	v_add_f32_e32 v7, v7, v22
	ds_bpermute_b32 v22, v36, v7
	s_waitcnt lgkmcnt(0)
	v_add_f32_e32 v7, v7, v22
	v_fmamk_f32 v7, v7, 0x3c000000, v249
	v_cmp_gt_f32_e32 vcc, s8, v7
	v_mul_f32_e32 v22, 0x4b800000, v7
	s_nop 0
	v_cndmask_b32_e32 v7, v7, v22, vcc
	v_rsq_f32_e32 v7, v7
	s_nop 0
	v_mul_f32_e32 v22, 0x45800000, v7
	v_cndmask_b32_e32 v22, v7, v22, vcc
	v_pk_mul_f32 v[8:9], v[22:23], v[8:9] op_sel_hi:[0,1]
	v_cmp_lt_i32_e32 vcc, s4, v0
	s_or_b64 s[2:3], vcc, s[2:3]
	v_pk_mul_f32 v[8:9], v[48:49], v[8:9]
	v_pk_mul_f32 v[14:15], v[22:23], v[28:29] op_sel_hi:[0,1]
	v_pk_mul_f32 v[14:15], v[50:51], v[14:15]
	v_cvt_pk_bf16_f32 v8, v8, v9
	v_cvt_pk_bf16_f32 v9, v14, v15
	v_pk_mul_f32 v[14:15], v[22:23], v[24:25] op_sel_hi:[0,1]
	v_pk_mul_f32 v[10:11], v[44:45], v[14:15]
	v_pk_mul_f32 v[14:15], v[22:23], v[20:21] op_sel_hi:[0,1]
	v_pk_mul_f32 v[12:13], v[46:47], v[14:15]
	v_cvt_pk_bf16_f32 v10, v10, v11
	v_cvt_pk_bf16_f32 v11, v12, v13
	global_store_dwordx4 v[18:19], v[8:11], off
	s_waitcnt vmcnt(1)
	s_nop 1
	v_mov_b32_e32 v8, v40
	v_mov_b32_e32 v9, v41
	v_mov_b32_e32 v10, v42
	v_mov_b32_e32 v11, v43
	v_mov_b32_e32 v18, v52
	v_mov_b32_e32 v19, v53
	s_andn2_b64 exec, exec, s[2:3]
	s_cbranch_execnz .LBB0_364

; #define TIDX launder((int)threadIdx.x)
; DI float bf2f(bf16_t v) { return __uint_as_float(((unsigned)v) << 16); }
; DI unsigned pk2(float lo, float hi) { const f32x2g f = {lo, hi}; const hwbf16x2g r = __builtin_convertvector(f, hwbf16x2g); return __builtin_bit_cast(unsigned, r); }
; DI float shx(float v, int mask) { return __int_as_float(__builtin_amdgcn_ds_bpermute((lane_now() ^ mask) << 2, __float_as_int(v))); }
; DI void headnorm_rows(bf16_t* buf, int rows, const float* __restrict__ gain, int item0, int nitems_total) {
;   const int lane = TIDX & 63, gw = blockIdx.x * 8 + (TIDX >> 6), nw = gridDim.x * 8;
;   const int sub = lane >> 4, l16 = lane & 15;
;   (void)item0; (void)nitems_total;
;   for (int it = gw; it < rows / 4; it += nw) {
;     bf16_t* rp = buf + (size_t)(it * 4 + sub) * 128 + l16 * 8;
;     bf16x8 raw = *(const bf16x8*)rp;
;     float f[8], s = 0.f;
; #pragma unroll
;     for (int e = 0; e < 8; ++e) { f[e] = bf2f((bf16_t)raw[e]); s += f[e] * f[e]; }
;     s += shx(s, 1); s += shx(s, 2); s += shx(s, 4); s += shx(s, 8);
;     const float rs = rsqrtf(s * (1.f / 128.f) + EPS_);
;     u32x4 o;
;     o.x = pk2(f[0] * rs * gain[l16 * 8 + 0], f[1] * rs * gain[l16 * 8 + 1]); o.y = pk2(f[2] * rs * gain[l16 * 8 + 2], f[3] * rs * gain[l16 * 8 + 3]);
;     o.z = pk2(f[4] * rs * gain[l16 * 8 + 4], f[5] * rs * gain[l16 * 8 + 5]); o.w = pk2(f[6] * rs * gain[l16 * 8 + 6], f[7] * rs * gain[l16 * 8 + 7]);
;     *(u32x4*)rp = o;
;   }
; DI void run_phase(const Params& p0, int ph) {
;     ...
;         if (layer == 0) for (int l = 0; l < 4; ++l) headnorm_rows((bf16_t*)(ws + A_MEMK) + (size_t)l * 8 * 256 * 128, 8 * 256, p.in[27] + l * 128, 0, 0);
.LBB0_368:
	v_mov_b32_e32 v2, v199
	v_mov_b32_e32 v0, v199
	v_readlane_b32 s0, v250, 11
	v_ashrrev_i32_e32 v6, 6, v0
	s_nop 0
	v_add_u32_e32 v0, s0, v6
	s_movk_i32 s0, 0x200
	v_cmp_gt_i32_e32 vcc, s0, v0
	s_and_saveexec_b64 s[0:1], vcc
	v_readlane_b32 s24, v252, 43
	v_readlane_b32 s25, v252, 44
	v_readlane_b32 s25, v252, 36
	s_mov_b32 s26, 0x800000
	s_movk_i32 s27, 0x1ff
	s_cbranch_execz .LBB0_367
	v_readlane_b32 s2, v253, 10
	v_readlane_b32 s3, v253, 11
	s_lshl_b32 s2, s6, 7
	v_readlane_b32 s8, v250, 41
	s_mov_b32 s7, s3
	s_lshl_b64 s[2:3], s[2:3], 2
	v_readlane_b32 s14, v250, 47
	v_bfe_u32 v7, v2, 4, 2
	v_writelane_b32 v253, s6, 10
	v_readlane_b32 s15, v250, 48
	s_add_u32 s2, s14, s2
	v_lshlrev_b32_e32 v2, 3, v2
	v_writelane_b32 v253, s7, 11
	s_addc_u32 s3, s15, s3
	s_lshl_b32 s7, s6, 19
	v_and_b32_e32 v4, 0x78, v2
	v_readlane_b32 s9, v250, 42
	s_add_u32 s8, s4, s7
	v_lshlrev_b32_e32 v2, 1, v4
	v_lshlrev_b32_e32 v4, 2, v4
	v_mov_b32_e32 v5, v1
	s_addc_u32 s9, s5, 0
	s_waitcnt lgkmcnt(0)
	v_mov_b32_e32 v3, v1
	v_lshl_add_u64 v[4:5], s[2:3], 0, v[4:5]
	v_lshlrev_b32_e32 v6, 2, v6
	v_readlane_b32 s2, v252, 35
	v_lshl_add_u64 v[2:3], s[8:9], 0, v[2:3]
	v_readlane_b32 s10, v250, 43
	v_add3_u32 v6, s2, v6, v7
	s_mov_b64 s[2:3], 0
	v_readlane_b32 s11, v250, 44
	v_readlane_b32 s12, v250, 45
	v_readlane_b32 s13, v250, 46
	v_readlane_b32 s16, v250, 49
	v_readlane_b32 s17, v250, 50
	v_readlane_b32 s18, v250, 51
	v_readlane_b32 s19, v250, 52
	v_readlane_b32 s20, v250, 53
	v_readlane_b32 s21, v250, 54
	v_readlane_b32 s22, v250, 55
	v_readlane_b32 s23, v250, 56
	global_load_dwordx4 v[44:47], v[4:5], off offset:16
	global_load_dwordx4 v[48:51], v[4:5], off
	v_ashrrev_i32_e32 v7, 31, v6
	v_lshlrev_b64 v[8:9], 8, v[6:7]
	v_lshl_add_u64 v[18:19], v[2:3], 0, v[8:9]
	global_load_dwordx4 v[8:11], v[18:19], off
	s_waitcnt vmcnt(0)
.LBB0_370:
	v_add_u32_e32 v38, s25, v6
	v_ashrrev_i32_e32 v39, 31, v38
	v_lshlrev_b64 v[38:39], 8, v[38:39]
	v_lshl_add_u64 v[52:53], v[2:3], 0, v[38:39]
	global_load_dwordx4 v[40:43], v[52:53], off
	v_mov_b32_e32 v7, v199
	v_mov_b32_e32 v12, v199
	v_add_u32_e32 v0, s24, v0
	v_lshlrev_b32_e32 v12, 2, v12
	v_bitop3_b32 v34, v12, 8, v193 bitop3:0x6c
	v_mov_b32_e32 v12, v199
	v_lshlrev_b32_e32 v7, 2, v7
	v_lshlrev_b32_e32 v12, 2, v12
	v_bitop3_b32 v35, v12, 16, v193 bitop3:0x6c
	v_mov_b32_e32 v12, v199
	v_bitop3_b32 v7, v7, 4, v193 bitop3:0x6c
	v_lshlrev_b32_e32 v12, 2, v12
	v_bitop3_b32 v36, v12, 32, v193 bitop3:0x6c
	v_add_u32_e32 v6, s25, v6
	v_and_b32_e32 v21, 0xffff0000, v11
	v_lshlrev_b32_e32 v20, 16, v11
	v_and_b32_e32 v25, 0xffff0000, v10
	v_lshlrev_b32_e32 v24, 16, v10
	v_and_b32_e32 v29, 0xffff0000, v9
	v_lshlrev_b32_e32 v28, 16, v9
	v_and_b32_e32 v9, 0xffff0000, v8
	v_lshlrev_b32_e32 v8, 16, v8
	v_pk_mul_f32 v[32:33], v[8:9], v[8:9]
	v_pk_mul_f32 v[30:31], v[28:29], v[28:29]
	v_add_f32_e32 v32, v32, v33
	v_add_f32_e32 v30, v30, v32
	v_pk_mul_f32 v[26:27], v[24:25], v[24:25]
	v_add_f32_e32 v30, v31, v30
	v_add_f32_e32 v26, v26, v30
	v_pk_mul_f32 v[22:23], v[20:21], v[20:21]
	v_add_f32_e32 v26, v27, v26
	v_add_f32_e32 v22, v22, v26
	v_add_f32_e32 v22, v23, v22
	ds_bpermute_b32 v7, v7, v22
	s_waitcnt lgkmcnt(0)
	v_add_f32_e32 v7, v22, v7
	ds_bpermute_b32 v22, v34, v7
	s_waitcnt lgkmcnt(0)
	v_add_f32_e32 v7, v7, v22
	ds_bpermute_b32 v22, v35, v7
	s_waitcnt lgkmcnt(0)
	v_add_f32_e32 v7, v7, v22
	ds_bpermute_b32 v22, v36, v7
	s_waitcnt lgkmcnt(0)
	v_add_f32_e32 v7, v7, v22
	v_fmamk_f32 v7, v7, 0x3c000000, v249
	v_cmp_gt_f32_e32 vcc, s26, v7
	v_mul_f32_e32 v22, 0x4b800000, v7
	s_nop 0
	v_cndmask_b32_e32 v7, v7, v22, vcc
	v_rsq_f32_e32 v7, v7
	s_nop 0
	v_mul_f32_e32 v22, 0x45800000, v7
	v_cndmask_b32_e32 v22, v7, v22, vcc
	v_pk_mul_f32 v[8:9], v[22:23], v[8:9] op_sel_hi:[0,1]
	v_cmp_lt_i32_e32 vcc, s27, v0
	s_or_b64 s[2:3], vcc, s[2:3]
	v_pk_mul_f32 v[8:9], v[48:49], v[8:9]
	v_pk_mul_f32 v[14:15], v[22:23], v[28:29] op_sel_hi:[0,1]
	v_pk_mul_f32 v[14:15], v[50:51], v[14:15]
	v_cvt_pk_bf16_f32 v8, v8, v9
	v_cvt_pk_bf16_f32 v9, v14, v15
	v_pk_mul_f32 v[14:15], v[22:23], v[24:25] op_sel_hi:[0,1]
	v_pk_mul_f32 v[10:11], v[44:45], v[14:15]
	v_pk_mul_f32 v[14:15], v[22:23], v[20:21] op_sel_hi:[0,1]
	v_pk_mul_f32 v[12:13], v[46:47], v[14:15]
	v_cvt_pk_bf16_f32 v10, v10, v11
	v_cvt_pk_bf16_f32 v11, v12, v13
	global_store_dwordx4 v[18:19], v[8:11], off
	s_waitcnt vmcnt(1)
	s_nop 1
	v_mov_b32_e32 v8, v40
	v_mov_b32_e32 v9, v41
	v_mov_b32_e32 v10, v42
	v_mov_b32_e32 v11, v43
	v_mov_b32_e32 v18, v52
	v_mov_b32_e32 v19, v53
	s_andn2_b64 exec, exec, s[2:3]
	s_cbranch_execnz .LBB0_370
	s_branch .LBB0_367
